# V^T projection visits token-tile rounds in reverse order (re-reads rows most recently touched by K projection first)
# speedup vs baseline: 1.0067x; 1.0067x over previous
.LBB0_10:
	v_readlane_b32 s0, v254, 0
	s_cmp_le_i32 s75, s0
	s_cbranch_scc1 .LBB0_425
	s_add_u32 s76, s94, 0xa0
	s_addc_u32 s77, s95, 0
	s_lshl_b32 s98, s2, 3
	s_cmpk_lt_i32 s2, 0x400
	s_cselect_b64 s[96:97], -1, 0
	s_lshl_b32 s0, s2, 7
	v_writelane_b32 v254, s0, 1
	s_and_b32 s0, s0, 0x380
	s_ashr_i32 s1, s2, 3
	s_add_i32 s0, s0, s1
	s_ashr_i32 s4, s0, 2
	s_add_i32 s4, s4, 24
	s_lshl_b32 s0, s4, 8
	s_and_b32 s3, s1, 3
	v_writelane_b32 v254, s0, 2
	v_writelane_b32 v254, s3, 3
	s_lshl_b32 s0, s3, 19
	s_ashr_i32 s5, s4, 31
	v_writelane_b32 v254, s0, 4
	s_lshl_b64 s[6:7], s[4:5], 19
	v_writelane_b32 v254, s6, 5
	s_mov_b32 s0, s4
	s_ashr_i32 s5, s2, 31
	v_writelane_b32 v254, s7, 6
	v_writelane_b32 v254, s0, 7
	s_add_i32 s4, s4, -24
	s_and_b32 s3, s1, 7
	v_lshrrev_b32_e32 v1, 20, v0
	v_writelane_b32 v254, s1, 8
	s_and_b32 s0, s4, -8
	s_or_b32 s12, s0, s3
	s_lshl_b32 s6, s12, 8
	s_ashr_i32 s13, s12, 31
	s_bfe_u32 s4, s1, 0x20003
	v_writelane_b32 v254, s6, 9
	s_lshl_b64 s[6:7], s[12:13], 19
	s_lshr_b32 s0, s1, 3
	v_writelane_b32 v254, s6, 10
	s_mov_b32 s13, s4
	s_lshl_b32 s4, s4, 19
	v_writelane_b32 v254, s7, 11
	s_cmpk_lt_i32 s2, 0x1600
	v_writelane_b32 v254, s4, 12
	s_cselect_b64 s[6:7], -1, 0
	v_writelane_b32 v254, s6, 13
	s_add_i32 s4, s1, 0xfffffd80
	s_lshr_b32 s4, s4, 1
	v_writelane_b32 v254, s7, 14
	s_lshr_b32 s6, s1, 2
	s_ashr_i32 s7, s2, 8
	s_lshl_b32 s8, s2, 5
	s_and_b32 s4, s4, 0x7ffffff8
	s_and_b32 s6, s6, 24
	s_and_b32 s7, s7, -4
	s_and_b32 s8, s8, 0xe0
	s_add_i32 s9, s2, 1
	s_cmpk_lt_i32 s1, 0x280
	v_lshrrev_b32_e32 v0, 10, v0
	v_or_b32_e32 v0, v0, v1
	s_movk_i32 s1, 0x3ff
	s_cselect_b32 s4, s6, s4
	v_and_or_b32 v0, v0, s1, v190
	s_cselect_b32 s1, 3, 1
	s_cselect_b32 s7, s7, 20
	s_or_b32 s3, s4, s3
	s_and_b32 s0, s1, s0
	s_add_i32 s8, s3, s8
	v_writelane_b32 v254, s9, 15
	s_or_b32 s6, s0, s7
	s_lshl_b32 s0, s8, 8
	v_writelane_b32 v254, s0, 16
	s_lshl_b32 s0, s2, 1
	v_writelane_b32 v254, s0, 17
	s_lshl_b32 s0, s2, 12
	v_writelane_b32 v254, s0, 18
	s_lshl_b32 s0, s2, 6
	v_writelane_b32 v254, s0, 19
	s_lshl_b32 s0, s2, 8
	v_writelane_b32 v254, s0, 20
	s_lshl_b32 s0, s2, 9
	v_writelane_b32 v254, s0, 21
	s_add_i32 s0, s98, 0xd400
	v_writelane_b32 v254, s0, 22
	s_add_i32 s0, 0, 0x21004
	v_writelane_b32 v254, s0, 23
	v_cmp_eq_u32_e64 s[10:11], 0, v190
	v_readlane_b32 s0, v254, 0
	s_mov_b32 s51, 0
	v_writelane_b32 v254, s10, 24
	s_mov_b32 s4, s8
	s_mov_b32 s9, s51
	v_writelane_b32 v254, s11, 25
	v_cmp_eq_u32_e64 s[10:11], 0, v0
	s_lshl_b64 s[8:9], s[8:9], 19
	s_ashr_i32 s7, s6, 31
	v_writelane_b32 v254, s10, 26
	v_mbcnt_lo_u32_b32 v1, -1, 0
	s_movk_i32 s61, 0x1600
	v_writelane_b32 v254, s11, 27
	v_writelane_b32 v254, s4, 28
	s_movk_i32 s99, 0x1000
	v_mov_b32_e32 v49, 0
	v_writelane_b32 v254, s5, 29
	v_writelane_b32 v254, s8, 30
	s_mov_b32 s4, s6
	s_lshl_b64 s[6:7], s[6:7], 19
	v_writelane_b32 v254, s9, 31
	v_writelane_b32 v254, s4, 32
	s_mov_b32 s91, 0x10000
	s_add_i32 s62, 0, 0x10000
	v_writelane_b32 v254, s5, 33
	v_writelane_b32 v254, s6, 34
	s_mov_b32 s4, s12
	s_movk_i32 s88, 0x2000
	v_writelane_b32 v254, s7, 35
	v_writelane_b32 v254, s4, 36
	s_movk_i32 s90, 0x4000
	s_movk_i32 s84, 0x6000
	s_mov_b32 s85, 0x8000
	s_mov_b32 s89, 0xc000
	v_mov_b32_e32 v191, 0x358637bd
	s_mov_b32 s65, 0x5000000
	s_mov_b32 s66, 0xd000000
	s_mov_b32 s63, 0x40000
	s_mov_b32 s64, 0x48000
	v_mov_b32_e32 v226, 0x2000
	v_mov_b32_e32 v227, 1
	v_mov_b64_e32 v[192:193], 0x400
	v_mov_b64_e32 v[194:195], 0x3ff
	v_mbcnt_hi_u32_b32 v228, -1, v1
	v_mov_b64_e32 v[196:197], 0x15ff
	v_mov_b32_e32 v229, 0x108
	v_mov_b32_e32 v230, 0x420
	v_mov_b32_e32 v231, 0x840
	v_mov_b32_e32 v232, 0xc60
	v_mov_b32_e32 v233, 0x1080
	v_mov_b32_e32 v234, 0x14a0
	v_mov_b32_e32 v235, 0x18c0
	s_mov_b32 s67, 0x50000
	s_mov_b32 s57, 0xd001000
	s_mov_b32 s59, 0xd002000
	s_mov_b32 s43, 0xd003000
	s_movk_i32 s58, 0x5800
	s_mov_b64 s[70:71], 0x80
	v_writelane_b32 v254, s5, 37
	v_writelane_b32 v254, s13, 38
	s_branch .LBB0_14

.LBB0_36:
	s_add_i32 s0, s46, 1
	s_mul_i32 s6, s0, s1
	s_mul_hi_u32 s7, s0, s3
	s_add_i32 s7, s7, s6
	s_mul_i32 s6, s0, s3
	s_add_u32 s24, s6, s2
	s_addc_u32 s25, s7, s5
	v_cmp_gt_i64_e32 vcc, s[24:25], v[194:195]
	v_cmp_lt_i64_e64 s[6:7], s[24:25], v[192:193]
	s_cbranch_vccnz .LBB0_38
	s_lshl_b32 s20, s24, 7
	s_and_b32 s20, s20, 0x380
	s_ashr_i32 s21, s24, 3
	s_add_i32 s22, s20, s21
	s_xor_b32 s22, s22, 0x60
	s_and_b32 s20, s21, 3
	s_ashr_i32 s22, s22, 2

.LBB0_356:
	s_add_i32 s0, s72, 1
	s_cmp_ge_i32 s0, s75
	s_cselect_b64 s[6:7], -1, 0
	s_cmp_lt_i32 s0, s75
	s_cselect_b64 s[8:9], -1, 0
	s_add_i32 s47, s47, -9
	s_cmp_lt_u32 s47, -2
	s_cselect_b64 s[10:11], -1, 0
	s_and_b64 s[8:9], s[8:9], s[10:11]
	s_andn2_b64 vcc, exec, s[8:9]
	s_cbranch_vccnz .LBB0_13
	v_readlane_b32 s1, v254, 0
	s_cmp_lg_u32 s72, s1
	s_mov_b64 s[8:9], -1
	s_cbranch_scc0 .LBB0_411
	s_getreg_b32 s1, hwreg(HW_REG_XCC_ID, 0, 4)
	s_waitcnt vmcnt(0)
	s_waitcnt vmcnt(0) lgkmcnt(0)
	s_barrier
	s_mov_b64 s[8:9], exec
	v_readlane_b32 s10, v254, 24
	v_readlane_b32 s11, v254, 25
	s_and_b64 s[10:11], s[8:9], s[10:11]
	s_mov_b64 exec, s[10:11]
	s_cbranch_execz .LBB0_410
	s_add_i32 s4, 0, 0x21000
	v_mov_b32_e32 v0, s4
	s_waitcnt vmcnt(0) expcnt(0) lgkmcnt(0)
	ds_read_b32 v2, v0
	v_readlane_b32 s10, v254, 23
	s_and_b32 s1, s1, 15
	s_waitcnt lgkmcnt(0)
	v_cmp_ne_u32_e32 vcc, 0, v2
	v_mov_b32_e32 v0, s10
	ds_read_b32 v0, v0
	s_cbranch_vccnz .LBB0_374
	s_load_dwordx2 s[14:15], s[76:77], 0x4
	s_add_u32 s10, s78, 0x200200
	s_addc_u32 s11, s79, 0
	s_add_u32 s12, s78, 0x200400
	s_addc_u32 s13, s79, 0
	s_waitcnt lgkmcnt(0)
	s_mul_i32 s3, s14, s3
	s_add_u32 s14, s78, 0x200500
	s_mul_i32 s3, s3, s15
	s_addc_u32 s15, s79, 0
	s_add_u32 s16, s78, 0x200600
	s_addc_u32 s17, s79, 0
	s_add_u32 s18, s78, 0x200700
	s_addc_u32 s19, s79, 0
	s_add_u32 s20, s78, 0x200800
	s_addc_u32 s21, s79, 0
	s_add_u32 s22, s78, 0x200900
	s_addc_u32 s23, s79, 0
	s_add_u32 s24, s78, 0x200a00
	s_addc_u32 s25, s79, 0
	s_add_u32 s26, s78, 0x200b00
	s_addc_u32 s27, s79, 0
	s_add_u32 s28, s78, 0x200c00
	s_addc_u32 s29, s79, 0
	s_add_u32 s30, s78, 0x200d00
	s_addc_u32 s31, s79, 0
	s_add_u32 s34, s78, 0x200e00
	s_addc_u32 s35, s79, 0
	s_add_u32 s36, s78, 0x200f00
	s_addc_u32 s37, s79, 0
	s_add_u32 s38, s78, 0x201000
	s_addc_u32 s39, s79, 0
	s_add_u32 s40, s78, 0x201100
	s_addc_u32 s41, s79, 0
	s_add_u32 s52, s78, 0x201200
	s_addc_u32 s53, s79, 0
	s_add_u32 s80, s78, 0x201300
	s_addc_u32 s81, s79, 0
	s_mov_b32 s33, 1
	s_branch .LBB0_362
